# v13 + workgroups 0..15 prefetch their second (w_glu) transpose tile into L2 with one load when entering the transpose loop
# baseline (speedup 1.0000x reference)
; #define LAS __attribute__((address_space(3)))
; template <int MODE>
; __device__ __forceinline__ void transpose_item(const float* W, int K, int N, bf16_t* WT, const float* gain, LAS float* scr, int item, int lane) {
;     const int nblk = N / 32, kb = item / nblk, nb = item % nblk, k0 = 64 * kb, n0 = 32 * nb;
; #pragma unroll 8
;     for (int i = 0; i < 32; ++i) { const int kk = 2 * i + (lane >> 5); float w = W[(size_t)(k0 + kk) * N + n0 + (lane & 31)]; if (MODE == 0) w *= gain[k0 + kk]; scr[kk * 33 + (lane & 31)] = w; }
; __device__ __forceinline__ void phase_prep(const Params& p, LAS unsigned char* lds) {
;     ...
;         for (int it = gw; it < I_IN + I_OUT + I_GLU; it += NGW) {
;             int r = it;
;             if (r < I_IN) { transpose_item<0>(p.w_in, DM, NPROJ, (bf16_t*)(p.ws + WS_WINT), p.norm_gain, scr, r, lane); continue; } r -= I_IN;
;             if (r < I_OUT) { transpose_item<1>(p.w_out, DM, DM, (bf16_t*)(p.ws + WS_WOUTT), nullptr, scr, r, lane); continue; } r -= I_OUT;
;             transpose_item<1>(p.w_glu, 512, 512, (bf16_t*)(p.ws + WS_WGLUT), nullptr, scr, r, lane);
.LBB0_52:
	s_or_b64 exec, exec, s[8:9]
	s_movk_i32 s1, 0x880
	v_cmp_gt_i32_e32 vcc, s1, v18
	v_and_b32_e32 v212, 31, v0
	v_lshlrev_b32_e32 v19, 3, v0
	s_and_saveexec_b64 s[4:5], vcc
	s_cbranch_execz .LBB0_69
	v_readfirstlane_b32 s98, v0
	s_lshr_b32 s98, s98, 6
	s_lshl_b32 s99, s2, 3
	s_add_i32 s98, s98, s99
	s_cmp_lt_u32 s98, 0x80
	s_cbranch_scc0 .Lwglu_pf_skip
	s_lshr_b32 s99, s98, 4
	s_lshl_b32 s99, s99, 17
	s_and_b32 s100, s98, 15
	s_lshl_b32 s100, s100, 7
	s_add_i32 s99, s99, s100
	v_and_b32_e32 v200, 63, v0
	v_lshlrev_b32_e32 v200, 11, v200
	v_add_u32_e32 v200, s99, v200
	global_load_dword v201, v200, s[68:69]
.Lwglu_pf_skip:
	v_lshlrev_b32_e32 v3, 3, v0
	s_lshl_b32 s3, s2, 5
	s_movk_i32 s1, 0x2100
	v_lshrrev_b32_e32 v24, 3, v163
	v_and_b32_e32 v3, 56, v3
	s_and_b32 s3, s3, 0x3c0
	v_mad_u32_u24 v1, v28, s1, 0
	v_mul_u32_u24_e32 v5, 0x84, v3
	v_lshlrev_b32_e32 v7, 2, v24
	s_lshl_b32 s6, s3, 1
	v_readlane_b32 s8, v255, 0
	v_lshlrev_b32_e32 v4, 2, v212
	v_add3_u32 v7, v1, v5, v7
	v_mov_b32_e32 v5, 0
	v_readlane_b32 s9, v255, 1
	s_add_u32 s6, s8, s6
	v_add_u32_e32 v6, v1, v4
	v_lshl_add_u64 v[8:9], s[80:81], 0, v[4:5]
	s_addc_u32 s7, s9, 0
	v_lshlrev_b32_e32 v4, 1, v3
	v_lshl_add_u64 v[10:11], s[6:7], 0, v[4:5]
	s_mov_b64 s[6:7], 0x2800000
	v_lshl_add_u64 v[10:11], v[10:11], 0, s[6:7]
	v_lshl_add_u64 v[14:15], s[8:9], 0, v[4:5]
	s_mov_b64 s[6:7], 0x2600000
	v_lshrrev_b32_e32 v2, 5, v163
	v_lshl_add_u64 v[12:13], v[14:15], 0, s[6:7]
	s_mov_b64 s[6:7], 0x2000000
	s_movk_i32 s1, 0x84
	v_or_b32_e32 v25, 8, v24
	v_or_b32_e32 v29, 16, v24
	v_or_b32_e32 v30, 24, v24
	v_lshl_add_u64 v[14:15], v[14:15], 0, s[6:7]
	v_mov_b32_e32 v1, v2
	s_mov_b64 s[6:7], 0
	s_movk_i32 s14, 0x5ff
	s_movk_i32 s15, 0x7ff
	s_movk_i32 s16, 0x60
	s_movk_i32 s17, 0x103
	s_movk_i32 s18, 0x1000
	s_movk_i32 s19, 0x2000
	s_movk_i32 s20, 0x3000
	s_movk_i32 s21, 0x303
	s_movk_i32 s22, 0x4000
	s_mov_b32 s23, 0x2aaaaaab
	s_movk_i32 s24, 0xff03
	s_movk_i32 s25, 0x7f
	v_add_u32_e32 v31, 0xc000, v7
	s_branch .LBB0_55
